# scalar row-sum chains moved into the S-MFMA gaps (5 plain VALU per 32x32x16 gap)
# speedup vs baseline: 1.0182x; 1.0058x over previous
.LBB0_280:
	s_waitcnt lgkmcnt(5)
	v_mfma_f32_32x32x16_bf16 v[66:81], v[166:169], v[134:137], v[66:81]
	v_add_f32_e32 v174, v114, v115
	v_add_f32_e32 v175, v116, v117
	v_add_f32_e32 v176, v118, v119
	v_add_f32_e32 v177, v120, v121
	v_add_f32_e32 v174, v174, v122
	s_waitcnt lgkmcnt(4)
	v_mfma_f32_32x32x16_bf16 v[82:97], v[162:165], v[134:137], v[82:97]
	v_add_f32_e32 v175, v175, v123
	v_add_f32_e32 v176, v176, v124
	v_add_f32_e32 v177, v177, v125
	v_add_f32_e32 v174, v174, v126
	v_add_f32_e32 v175, v175, v127
	s_waitcnt lgkmcnt(3)
	v_mfma_f32_32x32x16_bf16 v[66:81], v[158:161], v[138:141], v[66:81]
	v_add_f32_e32 v176, v176, v128
	v_add_f32_e32 v177, v177, v129
	v_add_f32_e32 v174, v174, v98
	v_add_f32_e32 v175, v175, v99
	v_add_f32_e32 v176, v176, v100
	s_waitcnt lgkmcnt(2)
	v_mfma_f32_32x32x16_bf16 v[82:97], v[154:157], v[138:141], v[82:97]
	v_add_f32_e32 v177, v177, v101
	v_add_f32_e32 v174, v174, v102
	v_add_f32_e32 v175, v175, v103
	v_add_f32_e32 v176, v176, v104
	v_add_f32_e32 v177, v177, v105
	s_waitcnt lgkmcnt(1)
	v_mfma_f32_32x32x16_bf16 v[66:81], v[150:153], v[142:145], v[66:81]
	v_add_f32_e32 v174, v174, v106
	v_add_f32_e32 v175, v175, v107
	v_add_f32_e32 v176, v176, v108
	v_add_f32_e32 v177, v177, v109
	s_waitcnt lgkmcnt(0)
	v_mfma_f32_32x32x16_bf16 v[82:97], v[146:149], v[142:145], v[82:97]
	v_add_f32_e32 v174, v174, v110
	v_add_f32_e32 v175, v175, v111
	v_add_f32_e32 v176, v176, v112
	v_add_f32_e32 v177, v177, v113
	v_add_f32_e32 v174, v174, v175
	v_add_f32_e32 v176, v176, v177
	v_cvt_pk_bf16_f32 v113, v112, v113
	v_cvt_pk_bf16_f32 v112, v110, v111
	v_cvt_pk_bf16_f32 v111, v108, v109
	v_cvt_pk_bf16_f32 v110, v106, v107
	v_add_f32_e32 v174, v174, v176
	v_cvt_pk_bf16_f32 v109, v104, v105
	v_cvt_pk_bf16_f32 v108, v102, v103
	v_cvt_pk_bf16_f32 v107, v100, v101
	v_cvt_pk_bf16_f32 v106, v98, v99
	v_cvt_pk_bf16_f32 v98, v114, v115
	v_cvt_pk_bf16_f32 v99, v116, v117
	v_cvt_pk_bf16_f32 v100, v118, v119
	v_cvt_pk_bf16_f32 v101, v120, v121
	v_cvt_pk_bf16_f32 v102, v122, v123
	v_cvt_pk_bf16_f32 v103, v124, v125
	v_cvt_pk_bf16_f32 v104, v126, v127
	v_cvt_pk_bf16_f32 v105, v128, v129
	v_add_f32_e32 v213, v174, v0
	ds_read_b128 v[114:117], v208 offset:49152
	ds_read_b128 v[118:121], v208 offset:53248
	ds_read_b128 v[122:125], v208 offset:57344
	ds_read_b128 v[126:129], v208 offset:61440
	ds_read_b128 v[150:153], v209 offset:53248
	ds_read_b128 v[146:149], v209 offset:49152
	ds_read_b128 v[154:157], v209 offset:57344
	ds_read_b128 v[158:161], v209 offset:61440
	s_and_b32 s0, s77, 0x3f0000
	s_lshl_b32 s22, s0, 1
	s_mov_b32 m0, s73
	v_lshl_add_u64 v[164:165], v[188:189], 0, s[22:23]
	global_load_lds_dwordx4 v[164:165], off
	v_lshl_add_u64 v[164:165], v[192:193], 0, s[22:23]
	s_mov_b32 m0, s31
	s_lshl_b32 s22, s15, 1
	global_load_lds_dwordx4 v[164:165], off
	v_lshl_add_u64 v[164:165], v[190:191], 0, s[22:23]
	s_mov_b32 m0, s71
	global_load_lds_dwordx4 v[164:165], off
	v_lshl_add_u64 v[164:165], v[194:195], 0, s[22:23]
	s_mov_b32 m0, s72
	s_nop 0
	global_load_lds_dwordx4 v[164:165], off
	s_waitcnt lgkmcnt(0)
	v_mfma_f32_32x32x16_bf16 v[50:65], v[98:101], v[114:117], v[50:65]
	ds_read_b128 v[114:117], v210 offset:53248
	v_exp_f32_e32 v66, v66
	v_exp_f32_e32 v67, v67
	v_mfma_f32_32x32x16_bf16 v[34:49], v[98:101], v[118:121], v[34:49]
	ds_read_b128 v[118:121], v210 offset:57344
	v_exp_f32_e32 v68, v68
	v_exp_f32_e32 v69, v69
	v_mfma_f32_32x32x16_bf16 v[18:33], v[98:101], v[122:125], v[18:33]
	ds_read_b128 v[122:125], v210 offset:61440
	v_exp_f32_e32 v70, v70
	v_exp_f32_e32 v71, v71
	v_mfma_f32_32x32x16_bf16 v[2:17], v[98:101], v[126:129], v[2:17]
	ds_read_b128 v[98:101], v210 offset:49152
	v_exp_f32_e32 v72, v72
	v_exp_f32_e32 v73, v73
	v_mfma_f32_32x32x16_bf16 v[50:65], v[102:105], v[146:149], v[50:65]
	ds_read_b128 v[126:129], v212 offset:53248
	v_exp_f32_e32 v74, v74
	v_exp_f32_e32 v75, v75
	v_mfma_f32_32x32x16_bf16 v[34:49], v[102:105], v[150:153], v[34:49]
	ds_read_b128 v[146:149], v212 offset:57344
	v_exp_f32_e32 v76, v76
	v_exp_f32_e32 v77, v77
	v_mfma_f32_32x32x16_bf16 v[18:33], v[102:105], v[154:157], v[18:33]
	ds_read_b128 v[150:153], v212 offset:61440
	v_exp_f32_e32 v78, v78
	v_exp_f32_e32 v79, v79
	v_mfma_f32_32x32x16_bf16 v[2:17], v[102:105], v[158:161], v[2:17]
	ds_read_b128 v[102:105], v212 offset:49152
	v_exp_f32_e32 v80, v80
	v_exp_f32_e32 v81, v81
	s_waitcnt lgkmcnt(0)
	v_mfma_f32_32x32x16_bf16 v[50:65], v[106:109], v[98:101], v[50:65]
	v_exp_f32_e32 v82, v82
	v_exp_f32_e32 v83, v83
	v_mfma_f32_32x32x16_bf16 v[34:49], v[106:109], v[114:117], v[34:49]
	v_exp_f32_e32 v84, v84
	v_exp_f32_e32 v85, v85
	v_mfma_f32_32x32x16_bf16 v[18:33], v[106:109], v[118:121], v[18:33]
	v_exp_f32_e32 v86, v86
	v_exp_f32_e32 v87, v87
	v_mfma_f32_32x32x16_bf16 v[2:17], v[106:109], v[122:125], v[2:17]
	v_exp_f32_e32 v88, v88
	v_exp_f32_e32 v89, v89
	v_mfma_f32_32x32x16_bf16 v[50:65], v[110:113], v[102:105], v[50:65]
	v_exp_f32_e32 v90, v90
	v_exp_f32_e32 v91, v91
	v_mfma_f32_32x32x16_bf16 v[34:49], v[110:113], v[126:129], v[34:49]
	v_exp_f32_e32 v92, v92
	v_exp_f32_e32 v93, v93
	v_mfma_f32_32x32x16_bf16 v[18:33], v[110:113], v[146:149], v[18:33]
	v_exp_f32_e32 v94, v94
	v_exp_f32_e32 v95, v95
	v_mfma_f32_32x32x16_bf16 v[2:17], v[110:113], v[150:153], v[2:17]
	v_exp_f32_e32 v96, v96
	v_exp_f32_e32 v97, v97
	s_waitcnt vmcnt(0)
	s_add_i32 s76, s76, 2
	s_add_i32 s77, s77, 0x20000
	s_cmp_gt_u32 s76, 61
	s_waitcnt vmcnt(0)
	s_barrier
	s_cbranch_scc1 .LBB0_295

.LBB0_288:
	s_waitcnt lgkmcnt(5)
	v_mfma_f32_32x32x16_bf16 v[114:129], v[166:169], v[134:137], v[114:129]
	v_add_f32_e32 v174, v66, v67
	v_add_f32_e32 v175, v68, v69
	v_add_f32_e32 v176, v70, v71
	v_add_f32_e32 v177, v72, v73
	v_add_f32_e32 v174, v174, v74
	s_waitcnt lgkmcnt(4)
	v_mfma_f32_32x32x16_bf16 v[98:113], v[162:165], v[134:137], v[98:113]
	v_add_f32_e32 v175, v175, v75
	v_add_f32_e32 v176, v176, v76
	v_add_f32_e32 v177, v177, v77
	v_add_f32_e32 v174, v174, v78
	v_add_f32_e32 v175, v175, v79
	s_waitcnt lgkmcnt(3)
	v_mfma_f32_32x32x16_bf16 v[114:129], v[158:161], v[138:141], v[114:129]
	v_add_f32_e32 v176, v176, v80
	v_add_f32_e32 v177, v177, v81
	v_add_f32_e32 v174, v174, v82
	v_add_f32_e32 v175, v175, v83
	v_add_f32_e32 v176, v176, v84
	s_waitcnt lgkmcnt(2)
	v_mfma_f32_32x32x16_bf16 v[98:113], v[154:157], v[138:141], v[98:113]
	v_add_f32_e32 v177, v177, v85
	v_add_f32_e32 v174, v174, v86
	v_add_f32_e32 v175, v175, v87
	v_add_f32_e32 v176, v176, v88
	v_add_f32_e32 v177, v177, v89
	s_waitcnt lgkmcnt(1)
	v_mfma_f32_32x32x16_bf16 v[114:129], v[150:153], v[142:145], v[114:129]
	v_add_f32_e32 v174, v174, v90
	v_add_f32_e32 v175, v175, v91
	v_add_f32_e32 v176, v176, v92
	v_add_f32_e32 v177, v177, v93
	s_waitcnt lgkmcnt(0)
	v_mfma_f32_32x32x16_bf16 v[98:113], v[146:149], v[142:145], v[98:113]
	v_add_f32_e32 v174, v174, v94
	v_add_f32_e32 v175, v175, v95
	v_add_f32_e32 v176, v176, v96
	v_add_f32_e32 v177, v177, v97
	v_add_f32_e32 v174, v174, v175
	v_add_f32_e32 v176, v176, v177
	v_cvt_pk_bf16_f32 v66, v66, v67
	v_cvt_pk_bf16_f32 v67, v68, v69
	v_cvt_pk_bf16_f32 v68, v70, v71
	v_cvt_pk_bf16_f32 v69, v72, v73
	v_add_f32_e32 v174, v174, v176
	v_cvt_pk_bf16_f32 v70, v74, v75
	v_cvt_pk_bf16_f32 v71, v76, v77
	v_cvt_pk_bf16_f32 v72, v78, v79
	v_cvt_pk_bf16_f32 v73, v80, v81
	v_cvt_pk_bf16_f32 v74, v82, v83
	v_cvt_pk_bf16_f32 v75, v84, v85
	v_cvt_pk_bf16_f32 v76, v86, v87
	v_cvt_pk_bf16_f32 v77, v88, v89
	v_cvt_pk_bf16_f32 v78, v90, v91
	v_cvt_pk_bf16_f32 v79, v92, v93
	v_cvt_pk_bf16_f32 v80, v94, v95
	v_cvt_pk_bf16_f32 v81, v96, v97
	v_add_f32_e32 v0, v174, v213
	ds_read_b128 v[82:85], v208 offset:32768
	ds_read_b128 v[86:89], v208 offset:36864
	ds_read_b128 v[90:93], v208 offset:40960
	ds_read_b128 v[94:97], v208 offset:45056
	ds_read_b128 v[146:149], v209 offset:32768
	ds_read_b128 v[150:153], v209 offset:36864
	ds_read_b128 v[154:157], v209 offset:40960
	ds_read_b128 v[158:161], v209 offset:45056
	s_add_i32 s14, s77, 0xffff0000
	s_and_b32 s14, s14, 0x3e0000
	s_lshl_b32 s22, s14, 1
	s_mov_b32 m0, s70
	v_lshl_add_u64 v[164:165], v[188:189], 0, s[22:23]
	global_load_lds_dwordx4 v[164:165], off
	v_lshl_add_u64 v[164:165], v[192:193], 0, s[22:23]
	s_mov_b32 m0, s29
	s_lshl_b32 s22, s80, 1
	global_load_lds_dwordx4 v[164:165], off
	v_lshl_add_u64 v[164:165], v[190:191], 0, s[22:23]
	s_add_i32 m0, s70, 0xc000
	global_load_lds_dwordx4 v[164:165], off
	v_lshl_add_u64 v[164:165], v[194:195], 0, s[22:23]
	s_add_i32 m0, s70, 0xc400
	s_nop 0
	global_load_lds_dwordx4 v[164:165], off
	s_waitcnt lgkmcnt(0)
	v_mfma_f32_32x32x16_bf16 v[50:65], v[66:69], v[82:85], v[50:65]
	ds_read_b128 v[82:85], v210 offset:32768
	v_exp_f32_e32 v114, v114
	v_exp_f32_e32 v115, v115
	v_mfma_f32_32x32x16_bf16 v[34:49], v[66:69], v[86:89], v[34:49]
	ds_read_b128 v[86:89], v210 offset:36864
	v_exp_f32_e32 v116, v116
	v_exp_f32_e32 v117, v117
	v_mfma_f32_32x32x16_bf16 v[18:33], v[66:69], v[90:93], v[18:33]
	ds_read_b128 v[90:93], v210 offset:40960
	v_exp_f32_e32 v118, v118
	v_exp_f32_e32 v119, v119
	v_mfma_f32_32x32x16_bf16 v[2:17], v[66:69], v[94:97], v[2:17]
	ds_read_b128 v[66:69], v210 offset:45056
	v_exp_f32_e32 v120, v120
	v_exp_f32_e32 v121, v121
	v_mfma_f32_32x32x16_bf16 v[50:65], v[70:73], v[146:149], v[50:65]
	ds_read_b128 v[94:97], v212 offset:32768
	v_exp_f32_e32 v122, v122
	v_exp_f32_e32 v123, v123
	v_mfma_f32_32x32x16_bf16 v[34:49], v[70:73], v[150:153], v[34:49]
	ds_read_b128 v[146:149], v212 offset:36864
	v_exp_f32_e32 v124, v124
	v_exp_f32_e32 v125, v125
	v_mfma_f32_32x32x16_bf16 v[18:33], v[70:73], v[154:157], v[18:33]
	ds_read_b128 v[150:153], v212 offset:40960
	v_exp_f32_e32 v126, v126
	v_exp_f32_e32 v127, v127
	v_mfma_f32_32x32x16_bf16 v[2:17], v[70:73], v[158:161], v[2:17]
	ds_read_b128 v[70:73], v212 offset:45056
	v_exp_f32_e32 v128, v128
	v_exp_f32_e32 v129, v129
	s_waitcnt lgkmcnt(0)
	v_mfma_f32_32x32x16_bf16 v[50:65], v[74:77], v[82:85], v[50:65]
	v_exp_f32_e32 v98, v98
	v_exp_f32_e32 v99, v99
	v_mfma_f32_32x32x16_bf16 v[34:49], v[74:77], v[86:89], v[34:49]
	v_exp_f32_e32 v100, v100
	v_exp_f32_e32 v101, v101
	v_mfma_f32_32x32x16_bf16 v[18:33], v[74:77], v[90:93], v[18:33]
	v_exp_f32_e32 v102, v102
	v_exp_f32_e32 v103, v103
	v_mfma_f32_32x32x16_bf16 v[2:17], v[74:77], v[66:69], v[2:17]
	v_exp_f32_e32 v104, v104
	v_exp_f32_e32 v105, v105
	v_mfma_f32_32x32x16_bf16 v[50:65], v[78:81], v[94:97], v[50:65]
	v_exp_f32_e32 v106, v106
	v_exp_f32_e32 v107, v107
	v_mfma_f32_32x32x16_bf16 v[34:49], v[78:81], v[146:149], v[34:49]
	v_exp_f32_e32 v108, v108
	v_exp_f32_e32 v109, v109
	v_mfma_f32_32x32x16_bf16 v[18:33], v[78:81], v[150:153], v[18:33]
	v_exp_f32_e32 v110, v110
	v_exp_f32_e32 v111, v111
	v_mfma_f32_32x32x16_bf16 v[2:17], v[78:81], v[70:73], v[2:17]
	v_exp_f32_e32 v112, v112
	v_exp_f32_e32 v113, v113
	s_and_b64 s[0:1], s[0:1], exec
	s_waitcnt vmcnt(0)
	s_cselect_b32 s14, 1, 2
	s_and_b64 s[0:1], s[40:41], exec
	s_cselect_b32 s14, s14, 0
	s_cmp_eq_u32 s14, s79
	s_waitcnt vmcnt(0)
	s_barrier
	s_cbranch_scc1 .LBB0_290
	s_cmp_eq_u32 s79, 0
	s_cselect_b64 vcc, -1, 0
	s_cmp_eq_u32 s79, 2
	s_cselect_b64 s[0:1], -1, 0
	v_cndmask_b32_e64 v66, 0, v201, s[0:1]
	s_cmp_eq_u32 s14, 2
	v_cndmask_b32_e32 v66, v66, v200, vcc
	s_cselect_b64 vcc, -1, 0
	v_cndmask_b32_e32 v67, 0, v201, vcc
	v_cndmask_b32_e64 v67, v200, v67, s[40:41]
	v_sub_f32_e32 v66, v66, v67
	v_exp_f32_e32 v66, v66
	s_nop 0
	v_pk_mul_f32 v[64:65], v[66:67], v[64:65] op_sel_hi:[0,1]
	v_pk_mul_f32 v[62:63], v[66:67], v[62:63] op_sel_hi:[0,1]
	v_pk_mul_f32 v[60:61], v[66:67], v[60:61] op_sel_hi:[0,1]
	v_pk_mul_f32 v[58:59], v[66:67], v[58:59] op_sel_hi:[0,1]
	v_pk_mul_f32 v[56:57], v[66:67], v[56:57] op_sel_hi:[0,1]
	v_pk_mul_f32 v[54:55], v[66:67], v[54:55] op_sel_hi:[0,1]
	v_pk_mul_f32 v[52:53], v[66:67], v[52:53] op_sel_hi:[0,1]
	v_pk_mul_f32 v[50:51], v[66:67], v[50:51] op_sel_hi:[0,1]
	v_pk_mul_f32 v[48:49], v[66:67], v[48:49] op_sel_hi:[0,1]
	v_pk_mul_f32 v[46:47], v[66:67], v[46:47] op_sel_hi:[0,1]
	v_pk_mul_f32 v[44:45], v[66:67], v[44:45] op_sel_hi:[0,1]
	v_pk_mul_f32 v[42:43], v[66:67], v[42:43] op_sel_hi:[0,1]
	v_pk_mul_f32 v[40:41], v[66:67], v[40:41] op_sel_hi:[0,1]
	v_pk_mul_f32 v[38:39], v[66:67], v[38:39] op_sel_hi:[0,1]
	v_pk_mul_f32 v[36:37], v[66:67], v[36:37] op_sel_hi:[0,1]
	v_pk_mul_f32 v[34:35], v[66:67], v[34:35] op_sel_hi:[0,1]
	v_pk_mul_f32 v[32:33], v[66:67], v[32:33] op_sel_hi:[0,1]
	v_pk_mul_f32 v[30:31], v[66:67], v[30:31] op_sel_hi:[0,1]
	v_pk_mul_f32 v[28:29], v[66:67], v[28:29] op_sel_hi:[0,1]
	v_pk_mul_f32 v[26:27], v[66:67], v[26:27] op_sel_hi:[0,1]
	v_pk_mul_f32 v[24:25], v[66:67], v[24:25] op_sel_hi:[0,1]
	v_pk_mul_f32 v[22:23], v[66:67], v[22:23] op_sel_hi:[0,1]
	v_pk_mul_f32 v[20:21], v[66:67], v[20:21] op_sel_hi:[0,1]
	v_pk_mul_f32 v[18:19], v[66:67], v[18:19] op_sel_hi:[0,1]
	v_pk_mul_f32 v[16:17], v[66:67], v[16:17] op_sel_hi:[0,1]
	v_pk_mul_f32 v[14:15], v[66:67], v[14:15] op_sel_hi:[0,1]
	v_pk_mul_f32 v[12:13], v[66:67], v[12:13] op_sel_hi:[0,1]
	v_pk_mul_f32 v[10:11], v[66:67], v[10:11] op_sel_hi:[0,1]
	v_pk_mul_f32 v[8:9], v[66:67], v[8:9] op_sel_hi:[0,1]
	v_pk_mul_f32 v[6:7], v[66:67], v[6:7] op_sel_hi:[0,1]
	v_pk_mul_f32 v[4:5], v[66:67], v[4:5] op_sel_hi:[0,1]
	v_pk_mul_f32 v[2:3], v[66:67], v[2:3] op_sel_hi:[0,1]
	v_mul_f32_e32 v0, v0, v66
	s_branch .LBB0_291
